# attention loop: K/V LDS-DMA loads in SGPR-base form as well (10 VALU 64-bit adds per two steps removed)
# speedup vs baseline: 1.0039x; 1.0039x over previous
.LBB0_641:
	ds_read_b128 v[172:175], v214 offset:32768
	ds_read_b128 v[156:159], v214 offset:40960
	ds_read_b128 v[168:171], v215 offset:32768
	ds_read_b128 v[152:155], v215 offset:40960
	ds_read_b128 v[164:167], v216 offset:32768
	ds_read_b128 v[148:151], v216 offset:40960
	ds_read_b128 v[160:163], v217 offset:32768
	ds_read_b128 v[144:147], v217 offset:40960
	s_add_i32 s57, s58, 0x80
	s_and_b32 s59, s57, 0x780
	s_mul_i32 s10, s59, 0x1c00
	s_add_u32 s10, s12, s10
	s_addc_u32 s11, s55, 0
	s_mov_b64 s[100:101], s[10:11]
	s_add_u32 s98, s10, 0x400
	s_addc_u32 s99, s11, 0
	s_add_i32 s10, s58, 64
	s_and_b32 s60, s10, 0x7c0
	s_mul_i32 s10, s60, 0x1c00
	s_add_u32 s10, s12, s10
	s_mov_b32 m0, s41
	s_addc_u32 s11, s55, 0
	s_add_u32 s10, s10, 0x400
	s_addc_u32 s11, s11, 0
	global_load_lds_dwordx4 v190, s[100:101]
	s_mov_b32 m0, s42
	s_nop 0
	global_load_lds_dwordx4 v192, s[100:101]
	s_mov_b32 m0, s47
	s_nop 0
	global_load_lds_dwordx4 v190, s[10:11]
	s_mov_b32 m0, s48
	s_nop 0
	global_load_lds_dwordx4 v192, s[10:11]
	s_and_b32 s10, s58, 0x780
	s_sub_i32 s11, s10, s53
	s_add_i32 s61, s11, 0xffffff86
	v_sub_u32_e32 v96, s11, v203
	s_cmp_gt_u32 s61, 0xffffff0c
	v_lshl_add_u32 v96, v96, 2, v212
	s_cbranch_scc0 .LBB0_643
	ds_read2_b32 v[98:99], v96 offset0:160 offset1:161
	ds_read2_b32 v[100:101], v96 offset0:162 offset1:163
	ds_read2_b32 v[102:103], v96 offset0:168 offset1:169
	ds_read2_b32 v[104:105], v96 offset0:170 offset1:171
	s_waitcnt lgkmcnt(0)
	v_pk_add_f32 v[80:81], v[80:81], v[98:99]
	v_pk_add_f32 v[82:83], v[82:83], v[100:101]
	v_pk_add_f32 v[84:85], v[84:85], v[102:103]
	ds_read2_b32 v[98:99], v96 offset0:176 offset1:177
	ds_read2_b32 v[100:101], v96 offset0:178 offset1:179
	ds_read2_b32 v[102:103], v96 offset0:184 offset1:185
	ds_read2_b32 v[106:107], v96 offset0:186 offset1:187
	v_pk_add_f32 v[86:87], v[86:87], v[104:105]
	s_waitcnt lgkmcnt(0)
	v_pk_add_f32 v[88:89], v[88:89], v[98:99]
	v_pk_add_f32 v[90:91], v[90:91], v[100:101]
	v_pk_add_f32 v[92:93], v[92:93], v[102:103]
	v_pk_add_f32 v[94:95], v[94:95], v[106:107]

.LBB0_645:
	s_sub_i32 s61, s60, s53
	s_or_b32 s10, s61, 31
	s_cmpk_lt_i32 s10, 0xffa6
	s_cselect_b64 vcc, -1, 0
	s_cmpk_gt_i32 s61, 0x79
	s_cselect_b64 s[10:11], -1, 0
	v_cndmask_b32_e64 v96, 0, v185, s[10:11]
	s_or_b32 s10, s60, 32
	s_sub_i32 s60, s10, s53
	s_or_b32 s10, s60, 31
	s_cmpk_lt_i32 s10, 0xffa6
	v_cndmask_b32_e32 v112, v96, v184, vcc
	s_cselect_b64 vcc, -1, 0
	s_cmpk_gt_i32 s60, 0x79
	s_cselect_b64 s[10:11], -1, 0
	v_cndmask_b32_e64 v96, 0, v185, s[10:11]
	v_cndmask_b32_e32 v96, v96, v184, vcc
	v_mov_b32_e32 v113, v112
	v_mov_b64_e32 v[114:115], v[112:113]
	v_mov_b64_e32 v[116:117], v[112:113]
	v_mov_b64_e32 v[118:119], v[112:113]
	v_mov_b64_e32 v[120:121], v[112:113]
	v_mov_b64_e32 v[122:123], v[112:113]
	v_mov_b64_e32 v[124:125], v[112:113]
	v_mov_b64_e32 v[126:127], v[112:113]
	v_mov_b32_e32 v97, v96
	v_mov_b64_e32 v[98:99], v[96:97]
	v_mov_b64_e32 v[100:101], v[96:97]
	v_mov_b64_e32 v[102:103], v[96:97]
	v_mov_b64_e32 v[104:105], v[96:97]
	v_mov_b64_e32 v[106:107], v[96:97]
	v_mov_b64_e32 v[108:109], v[96:97]
	v_mov_b64_e32 v[110:111], v[96:97]
	s_waitcnt lgkmcnt(0)
	v_mfma_f32_32x32x16_bf16 v[112:127], v[172:175], v[140:143], v[112:127]
	ds_read_b64_tr_b16 v[218:219], v210 offset:16384
	ds_read_b64_tr_b16 v[220:221], v211 offset:18432
	v_exp_f32_e32 v80, v80
	v_exp_f32_e32 v81, v81
	v_mfma_f32_32x32x16_bf16 v[112:127], v[168:171], v[136:139], v[112:127]
	ds_read_b64_tr_b16 v[172:173], v208 offset:16384
	ds_read_b64_tr_b16 v[174:175], v209 offset:18432
	v_exp_f32_e32 v82, v82
	v_exp_f32_e32 v83, v83
	v_mfma_f32_32x32x16_bf16 v[112:127], v[164:167], v[132:135], v[112:127]
	ds_read_b64_tr_b16 v[168:169], v206 offset:16384
	ds_read_b64_tr_b16 v[170:171], v207 offset:18432
	v_exp_f32_e32 v84, v84
	v_exp_f32_e32 v85, v85
	v_mfma_f32_32x32x16_bf16 v[112:127], v[160:163], v[128:131], v[112:127]
	ds_read_b64_tr_b16 v[222:223], v204 offset:16384
	ds_read_b64_tr_b16 v[224:225], v205 offset:18432
	v_exp_f32_e32 v86, v86
	v_exp_f32_e32 v87, v87
	v_mfma_f32_32x32x16_bf16 v[96:111], v[156:159], v[140:143], v[96:111]
	ds_read_b64_tr_b16 v[160:161], v210 offset:20480
	ds_read_b64_tr_b16 v[162:163], v211 offset:22528
	v_exp_f32_e32 v88, v88
	v_exp_f32_e32 v89, v89
	v_mfma_f32_32x32x16_bf16 v[96:111], v[152:155], v[136:139], v[96:111]
	ds_read_b64_tr_b16 v[156:157], v208 offset:20480
	ds_read_b64_tr_b16 v[158:159], v209 offset:22528
	v_exp_f32_e32 v90, v90
	v_exp_f32_e32 v91, v91
	v_mfma_f32_32x32x16_bf16 v[96:111], v[148:151], v[132:135], v[96:111]
	ds_read_b64_tr_b16 v[152:153], v206 offset:20480
	ds_read_b64_tr_b16 v[154:155], v207 offset:22528
	v_exp_f32_e32 v92, v92
	v_exp_f32_e32 v93, v93
	v_mfma_f32_32x32x16_bf16 v[96:111], v[144:147], v[128:131], v[96:111]
	ds_read_b64_tr_b16 v[148:149], v204 offset:20480
	ds_read_b64_tr_b16 v[150:151], v205 offset:22528
	v_exp_f32_e32 v94, v94
	v_exp_f32_e32 v95, v95
	v_cvt_pk_bf16_f32 v144, v80, v81
	v_cvt_pk_bf16_f32 v145, v82, v83
	v_cvt_pk_bf16_f32 v146, v84, v85
	v_cvt_pk_bf16_f32 v147, v86, v87
	v_cvt_pk_bf16_f32 v226, v88, v89
	v_cvt_pk_bf16_f32 v227, v90, v91
	v_cvt_pk_bf16_f32 v228, v92, v93
	v_cvt_pk_bf16_f32 v229, v94, v95
	s_waitcnt lgkmcnt(14)
	v_mfma_f32_32x32x16_bf16 v[48:63], v[218:221], v[144:147], v[48:63]
	ds_read_b64_tr_b16 v[230:231], v210 offset:24576
	ds_read_b64_tr_b16 v[232:233], v211 offset:26624
	v_exp_f32_e32 v64, v64
	v_exp_f32_e32 v65, v65
	s_waitcnt lgkmcnt(14)
	v_mfma_f32_32x32x16_bf16 v[32:47], v[172:175], v[144:147], v[32:47]
	ds_read_b64_tr_b16 v[218:219], v208 offset:24576
	ds_read_b64_tr_b16 v[220:221], v209 offset:26624
	v_exp_f32_e32 v164, v66
	v_exp_f32_e32 v165, v67
	s_waitcnt lgkmcnt(14)
	v_mfma_f32_32x32x16_bf16 v[16:31], v[168:171], v[144:147], v[16:31]
	v_exp_f32_e32 v166, v68
	v_exp_f32_e32 v167, v69
	ds_read_b64_tr_b16 v[66:67], v206 offset:24576
	ds_read_b64_tr_b16 v[68:69], v207 offset:26624
	s_waitcnt lgkmcnt(14)
	v_mfma_f32_32x32x16_bf16 v[0:15], v[222:225], v[144:147], v[0:15]
	ds_read_b64_tr_b16 v[234:235], v204 offset:24576
	ds_read_b64_tr_b16 v[236:237], v205 offset:26624
	v_exp_f32_e32 v168, v70
	v_exp_f32_e32 v169, v71
	s_waitcnt lgkmcnt(14)
	v_mfma_f32_32x32x16_bf16 v[48:63], v[160:163], v[226:229], v[48:63]
	v_exp_f32_e32 v170, v72
	v_exp_f32_e32 v171, v73
	ds_read_b64_tr_b16 v[70:71], v210 offset:28672
	ds_read_b64_tr_b16 v[72:73], v211 offset:30720
	s_waitcnt lgkmcnt(14)
	v_mfma_f32_32x32x16_bf16 v[32:47], v[156:159], v[226:229], v[32:47]
	ds_read_b64_tr_b16 v[144:145], v208 offset:28672
	ds_read_b64_tr_b16 v[146:147], v209 offset:30720
	v_exp_f32_e32 v172, v74
	v_exp_f32_e32 v173, v75
	s_waitcnt lgkmcnt(14)
	v_mfma_f32_32x32x16_bf16 v[16:31], v[152:155], v[226:229], v[16:31]
	v_exp_f32_e32 v174, v76
	v_exp_f32_e32 v175, v77
	ds_read_b64_tr_b16 v[74:75], v206 offset:28672
	ds_read_b64_tr_b16 v[76:77], v207 offset:30720
	s_waitcnt lgkmcnt(14)
	v_mfma_f32_32x32x16_bf16 v[0:15], v[148:151], v[226:229], v[0:15]
	ds_read_b64_tr_b16 v[152:153], v204 offset:28672
	ds_read_b64_tr_b16 v[154:155], v205 offset:30720
	v_exp_f32_e32 v78, v78
	v_exp_f32_e32 v79, v79
	v_cvt_pk_bf16_f32 v148, v64, v65
	v_cvt_pk_bf16_f32 v149, v164, v165
	v_cvt_pk_bf16_f32 v150, v166, v167
	v_cvt_pk_bf16_f32 v151, v168, v169
	v_cvt_pk_bf16_f32 v156, v170, v171
	v_cvt_pk_bf16_f32 v157, v172, v173
	v_cvt_pk_bf16_f32 v158, v174, v175
	v_cvt_pk_bf16_f32 v159, v78, v79
	s_waitcnt lgkmcnt(14)
	v_mfma_f32_32x32x16_bf16 v[48:63], v[230:233], v[148:151], v[48:63]
	s_waitcnt lgkmcnt(12)
	v_mfma_f32_32x32x16_bf16 v[32:47], v[218:221], v[148:151], v[32:47]
	s_waitcnt lgkmcnt(10)
	v_mfma_f32_32x32x16_bf16 v[16:31], v[66:69], v[148:151], v[16:31]
	s_waitcnt lgkmcnt(8)
	v_mfma_f32_32x32x16_bf16 v[0:15], v[234:237], v[148:151], v[0:15]
	s_waitcnt lgkmcnt(6)
	v_mfma_f32_32x32x16_bf16 v[48:63], v[70:73], v[156:159], v[48:63]
	s_waitcnt lgkmcnt(4)
	v_mfma_f32_32x32x16_bf16 v[32:47], v[144:147], v[156:159], v[32:47]
	s_waitcnt lgkmcnt(2)
	v_mfma_f32_32x32x16_bf16 v[16:31], v[74:77], v[156:159], v[16:31]
	s_waitcnt lgkmcnt(0)
	v_mfma_f32_32x32x16_bf16 v[0:15], v[152:155], v[156:159], v[0:15]
	s_add_i32 s10, s58, 0xc0
	s_and_b32 s10, s10, 0x7c0
	s_mulk_i32 s10, 0x1c00
	s_add_u32 s10, s12, s10
	s_addc_u32 s11, s55, 0
	s_mov_b32 m0, s45
	s_waitcnt vmcnt(0) lgkmcnt(0)
	s_barrier
	ds_read_b128 v[160:163], v214
	ds_read_b128 v[156:159], v214 offset:8192
	ds_read_b128 v[74:77], v215
	ds_read_b128 v[152:155], v215 offset:8192
	ds_read_b128 v[70:73], v216
	ds_read_b128 v[148:151], v216 offset:8192
	ds_read_b128 v[144:147], v217 offset:8192
	global_load_lds_dwordx4 v190, s[10:11]
	s_mov_b32 m0, s46
	s_nop 0
	global_load_lds_dwordx4 v192, s[10:11]
	s_add_i32 s10, s61, 0xffffff86
	s_mov_b32 m0, s43
	v_sub_u32_e32 v194, s61, v203
	global_load_lds_dwordx4 v190, s[98:99]
	s_mov_b32 m0, s44
	s_cmp_lt_u32 s10, 0xffffff0d
	global_load_lds_dwordx4 v192, s[98:99]
	ds_read_b128 v[66:69], v217
	v_lshl_add_u32 v194, v194, 2, v212
	s_cbranch_scc1 .LBB0_647
	ds_read2_b32 v[196:197], v194 offset0:176 offset1:177
	ds_read2_b32 v[218:219], v194 offset0:178 offset1:179
	ds_read2_b32 v[220:221], v194 offset0:184 offset1:185
	ds_read2_b32 v[222:223], v194 offset0:186 offset1:187
	ds_read2_b32 v[224:225], v194 offset0:160 offset1:161
	ds_read2_b32 v[226:227], v194 offset0:162 offset1:163
	ds_read2_b32 v[228:229], v194 offset0:168 offset1:169
	ds_read2_b32 v[230:231], v194 offset0:170 offset1:171
	s_waitcnt lgkmcnt(0)
	v_pk_add_f32 v[126:127], v[126:127], v[222:223]
	v_pk_add_f32 v[124:125], v[124:125], v[220:221]
	v_pk_add_f32 v[122:123], v[122:123], v[218:219]
	v_pk_add_f32 v[120:121], v[120:121], v[196:197]
	v_pk_add_f32 v[118:119], v[118:119], v[230:231]
	v_pk_add_f32 v[116:117], v[116:117], v[228:229]
	v_pk_add_f32 v[114:115], v[114:115], v[226:227]
	v_pk_add_f32 v[112:113], v[112:113], v[224:225]
